# loop-edge edit: attention key-step loop back edge rotated (one taken branch per trip)
# speedup vs baseline: 1.0067x; 1.0067x over previous
; __device__ __forceinline__ void ph_attn(KP p, int l, unsigned char* sm, int wv) {
;     ...
;             for (int s = 0; s < 9; ++s) {
;                 const int kk0 = 16 * wid + 32 * s;
;                 f32x4 st[2];
; #pragma unroll
;                 for (int kt = 0; kt < 2; ++kt) {
;                     st[kt] = (f32x4){0.f, 0.f, 0.f, 0.f};
; #pragma unroll
;                     for (int ks = 0; ks < 2; ++ks) {
;                         const bf16x8 kf = *(const bf16x8*)(Ks + (kk0 + 16 * kt + fr) * 72 + 32 * ks + 8 * fq);
;                         st[kt] = __builtin_amdgcn_mfma_f32_16x16x32_bf16(kf, qf[ks], st[kt], 0, 0, 0);
;                     }
;                 }
;                 float sv[2][4]; float mx = -1e30f;
;                 if (interior && s >= 1 && s <= 7) {
; #pragma unroll
;                     for (int kt = 0; kt < 2; ++kt)
; #pragma unroll
;                         for (int r = 0; r < 4; ++r) { sv[kt][r] = st[kt][r]; mx = fmaxf(mx, sv[kt][r]); }
;                 } else {
; #pragma unroll
;                     for (int kt = 0; kt < 2; ++kt)
; #pragma unroll
;                         for (int r = 0; r < 4; ++r) {
;                             const int kk = kk0 + 16 * kt + 4 * fq + r, d = kk - 128 - qi, prel = Q0rel + kk - 128;
;                             const bool valid = d >= -128 && d <= 128 && prel >= 0 && prel < L && kk < 384;
;                             sv[kt][r] = valid ? st[kt][r] : -1e30f;
;                             mx = fmaxf(mx, sv[kt][r]);
;                         }
;                 }
;                 mx = fmaxf(mx, shx(mx, 16, lane)); mx = fmaxf(mx, shx(mx, 32, lane));
;                 const float mn = fmaxf(mrun, mx), alpha = __builtin_amdgcn_exp2f(mrun - mn);
;                 mrun = mn;
;                 float pr[2][4], psum = 0.f;
; #pragma unroll
;                 for (int kt = 0; kt < 2; ++kt)
; #pragma unroll
;                     for (int r = 0; r < 4; ++r) { pr[kt][r] = __builtin_amdgcn_exp2f(sv[kt][r] - mn); psum += pr[kt][r]; }
;                 lsum = lsum * alpha + psum;
;                 const bool rescale = __builtin_amdgcn_ballot_w64(alpha != 1.0f) != 0ull;
;                 union { bf16x8 v; unsigned u[4]; } pf;
;                 pf.u[0] = pk2(pr[0][0], pr[0][1]); pf.u[1] = pk2(pr[0][2], pr[0][3]); pf.u[2] = pk2(pr[1][0], pr[1][1]); pf.u[3] = pk2(pr[1][2], pr[1][3]);
; #pragma unroll
.LBB0_851:
	v_max_f32_e32 v59, v172, v172
	v_mov_b32_e32 v58, v59
	v_add_u32_e32 v172, 0, v161
	v_add_u32_e32 v222, 0xe000, v172
	ds_read2_b64 v[206:209], v222 offset0:40 offset1:44
	ds_read_b64 v[210:211], v222 offset:13248
	ds_read_b64 v[212:213], v222 offset:13280
	ds_read_b64 v[214:215], v222 offset:26176
	ds_read_b64 v[216:217], v222 offset:26208
	ds_read_b64 v[218:219], v222 offset:39104
	ds_read_b64 v[220:221], v222 offset:39136
	v_permlane16_swap_b32_e32 v59, v58
	v_add_u32_e32 v161, 64, v161
	v_add_u32_e32 v160, 0x1200, v160
	ds_read_b128 v[186:189], v160
	ds_read_b128 v[190:193], v160 offset:64
	ds_read_b128 v[194:197], v160 offset:2304
	ds_read_b128 v[198:201], v160 offset:2368
	v_max_f32_e32 v58, v59, v58
	v_mov_b32_e32 v59, v58
	s_nop 1
	v_permlane32_swap_b32_e32 v58, v59
	s_nop 0
	v_max3_f32 v63, v163, v58, v59
	v_sub_f32_e32 v59, v171, v63
	v_exp_f32_e32 v59, v59
	v_sub_f32_e32 v61, v170, v63
	v_exp_f32_e32 v61, v61
	v_sub_f32_e32 v62, v169, v63
	v_sub_f32_e32 v58, v163, v63
	v_exp_f32_e32 v64, v62
	v_sub_f32_e32 v62, v168, v63
	v_exp_f32_e32 v65, v62
	v_exp_f32_e32 v62, v58
	v_add_f32_e32 v60, 0, v59
	v_add_f32_e32 v60, v61, v60
	v_add_f32_e32 v60, v64, v60
	v_add_f32_e32 v163, v65, v60
	v_sub_f32_e32 v60, v166, v63
	v_cmp_neq_f32_e32 vcc, 1.0, v62
	v_exp_f32_e32 v168, v60
	v_sub_f32_e32 v60, v167, v63
	s_cmp_eq_u64 vcc, 0
	v_exp_f32_e32 v169, v60
	v_sub_f32_e32 v60, v164, v63
	s_cselect_b64 vcc, -1, 0
	v_cvt_pk_bf16_f32 v58, v59, v61
	v_cvt_pk_bf16_f32 v59, v64, v65
	v_pk_mul_f32 v[64:65], v[46:47], v[62:63] op_sel_hi:[1,0]
	v_exp_f32_e32 v170, v60
	v_sub_f32_e32 v60, v165, v63
	v_pk_mul_f32 v[164:165], v[48:49], v[62:63] op_sel_hi:[1,0]
	v_cndmask_b32_e32 v46, v64, v46, vcc
	v_exp_f32_e32 v171, v60
	v_cvt_pk_bf16_f32 v60, v168, v169
	v_cvt_pk_bf16_f32 v61, v170, v171
	v_cndmask_b32_e32 v49, v165, v49, vcc
	v_cndmask_b32_e32 v48, v164, v48, vcc
	v_cndmask_b32_e32 v47, v65, v47, vcc
	v_pk_mul_f32 v[64:65], v[62:63], v[52:53] op_sel_hi:[0,1]
	v_cndmask_b32_e32 v52, v64, v52, vcc
	s_waitcnt lgkmcnt(0)
	v_mfma_f32_16x16x32_bf16 v[46:49], v[206:209], v[58:61], v[46:49]
	v_mul_f32_e64 v164, v62, v50
	v_mul_f32_e64 v165, v62, v51
	v_cndmask_b32_e32 v51, v165, v51, vcc
	v_cndmask_b32_e32 v50, v164, v50, vcc
	v_cndmask_b32_e32 v53, v65, v53, vcc
	v_pk_mul_f32 v[64:65], v[62:63], v[44:45] op_sel_hi:[0,1]
	v_cndmask_b32_e32 v44, v64, v44, vcc
	s_nop 0
	v_mfma_f32_16x16x32_bf16 v[50:53], v[210:213], v[58:61], v[50:53]
	v_mul_f32_e64 v164, v62, v42
	v_mul_f32_e64 v165, v62, v43
	v_cndmask_b32_e32 v43, v165, v43, vcc
	v_cndmask_b32_e32 v42, v164, v42, vcc
	v_cndmask_b32_e32 v45, v65, v45, vcc
	v_pk_mul_f32 v[64:65], v[62:63], v[56:57] op_sel_hi:[0,1]
	v_cndmask_b32_e32 v56, v64, v56, vcc
	s_nop 0
	v_mfma_f32_16x16x32_bf16 v[42:45], v[214:217], v[58:61], v[42:45]
	v_mul_f32_e64 v164, v62, v54
	v_mul_f32_e64 v165, v62, v55
	v_cndmask_b32_e32 v55, v165, v55, vcc
	v_cndmask_b32_e32 v54, v164, v54, vcc
	v_cndmask_b32_e32 v57, v65, v57, vcc
	s_add_i32 s42, s42, 32
	s_cmpk_eq_i32 s42, 0xe0
	s_nop 0
	v_mfma_f32_16x16x32_bf16 v[54:57], v[218:221], v[58:61], v[54:57]
	v_add_f32_e32 v58, v168, v163
	v_add_f32_e32 v58, v169, v58
	v_add_f32_e32 v58, v170, v58
	v_add_f32_e32 v58, v171, v58
	v_fmac_f32_e32 v58, v162, v62
	v_mov_b32_e32 v163, v63
	v_mov_b32_e32 v162, v58
	s_cbranch_scc0 .LBB0_847
	s_branch .LBB0_837
